# GEMM main loops: one static s_setprio 1 for waves 4-7 (the half that runs one barrier behind) instead of per-segment priority toggles
# speedup vs baseline: 1.0069x; 1.0069x over previous
.LBB0_616:
	v_ashrrev_i32_e32 v1, 31, v8
	v_lshrrev_b32_e32 v1, 26, v1
	v_add_u32_e32 v1, v8, v1
	v_ashrrev_i32_e32 v9, 6, v1
	v_bfe_i32 v1, v8, 27, 1
	v_lshlrev_b32_e32 v0, 4, v8
	v_lshrrev_b32_e32 v1, 22, v1
	v_add_u32_e32 v1, v0, v1
	v_and_b32_e32 v1, 0xfffffc00, v1
	v_sub_u32_e32 v1, v0, v1
	v_lshrrev_b32_e32 v2, 4, v1
	v_bitop3_b32 v1, v2, v1, 32 bitop3:0x6c
	v_ashrrev_i32_e32 v3, 31, v1
	v_lshrrev_b32_e32 v3, 26, v3
	v_add_u32_e32 v3, v1, v3
	v_lshlrev_b32_e32 v2, 3, v9
	v_ashrrev_i32_e32 v10, 6, v3
	v_and_b32_e32 v3, 0xc0, v3
	v_and_b32_e32 v2, -16, v2
	v_sub_u32_e32 v1, v1, v3
	v_add_u32_e32 v2, v10, v2
	v_ashrrev_i16_sdwa v1, v230, sext(v1) dst_sel:DWORD dst_unused:UNUSED_PAD src0_sel:DWORD src1_sel:BYTE_0
	v_lshlrev_b32_e32 v4, 5, v9
	v_bfe_i32 v11, v1, 0, 16
	v_lshlrev_b32_e32 v1, 1, v2
	v_lshrrev_b32_e32 v3, 2, v2
	v_and_b32_e32 v5, 3, v10
	s_mov_b32 s6, 0xfffe0
	v_and_b32_e32 v4, 32, v4
	v_and_b32_e32 v1, 24, v1
	v_and_b32_e32 v3, 4, v3
	v_and_or_b32 v5, v2, s6, v5
	v_or3_b32 v1, v5, v3, v1
	v_add_lshl_u32 v3, v4, v11, 1
	v_add_u32_e32 v0, 0x2000, v0
	v_lshl_add_u32 v130, v1, 12, v3
	v_ashrrev_i32_e32 v1, 31, v0
	v_lshrrev_b32_e32 v1, 22, v1
	v_add_u32_e32 v1, v0, v1
	v_ashrrev_i32_e32 v12, 10, v1
	v_mul_i32_i24_e32 v1, 0x400, v12
	v_sub_u32_e32 v0, v0, v1
	v_lshrrev_b32_e32 v1, 4, v0
	v_bitop3_b32 v0, v1, v0, 32 bitop3:0x6c
	v_lshl_add_u32 v128, v2, 12, v3
	v_ashrrev_i32_e32 v2, 31, v0
	v_lshrrev_b32_e32 v2, 26, v2
	v_lshlrev_b32_e32 v1, 3, v12
	v_add_u32_e32 v2, v0, v2
	v_and_b32_e32 v1, -16, v1
	v_ashrrev_i32_e32 v13, 6, v2
	v_add_u32_e32 v1, v13, v1
	v_and_b32_e32 v4, 3, v13
	v_and_or_b32 v4, v1, s6, v4
	s_ashr_i32 s6, s8, 6
	s_ashr_i32 s7, s8, 8
	s_lshl_b32 s96, s6, 10
	s_add_u32 s26, s12, s38
	v_and_b32_e32 v2, 0xc0, v2
	s_addc_u32 s38, s13, s39
	s_ashr_i32 s57, s56, 31
	s_ashr_i32 s81, s80, 31
	v_sub_u32_e32 v0, v0, v2
	s_mov_b32 s46, s8
	s_lshl_b64 s[8:9], s[56:57], 20
	s_lshl_b64 s[30:31], s[80:81], 20
	v_ashrrev_i16_sdwa v0, v230, sext(v0) dst_sel:DWORD dst_unused:UNUSED_PAD src0_sel:DWORD src1_sel:BYTE_0
	s_add_u32 s90, s26, s30
	v_lshlrev_b32_e32 v3, 5, v12
	v_bfe_i32 v14, v0, 0, 16
	v_lshlrev_b32_e32 v0, 1, v1
	v_lshrrev_b32_e32 v2, 2, v1
	s_addc_u32 s91, s38, s31
	s_add_i32 s57, s96, 0
	v_and_b32_e32 v3, 32, v3
	v_and_b32_e32 v0, 24, v0
	v_and_b32_e32 v2, 4, v2
	s_add_i32 m0, s57, 0x10000
	v_or3_b32 v0, v4, v2, v0
	v_add_lshl_u32 v2, v3, v14, 1
	global_load_lds_dwordx4 v130, s[90:91]
	s_add_i32 m0, s57, 0x12000
	v_lshl_add_u32 v134, v0, 12, v2
	s_add_u32 s30, s90, 0x80000
	global_load_lds_dwordx4 v134, s[90:91]
	s_addc_u32 s31, s91, 0
	s_add_i32 m0, s57, 0x14000
	v_lshl_add_u32 v132, v1, 12, v2
	global_load_lds_dwordx4 v130, s[30:31]
	s_add_i32 m0, s57, 0x16000
	s_add_u32 s88, s22, s8
	s_addc_u32 s89, s23, s9
	s_add_i32 s97, s57, 0x2000
	global_load_lds_dwordx4 v134, s[30:31]
	s_mov_b32 m0, s57
	s_add_u32 s8, s88, 0x80000
	global_load_lds_dwordx4 v128, s[88:89]
	s_mov_b32 m0, s97
	s_addc_u32 s9, s89, 0
	s_add_i32 s93, s57, 0x4000
	global_load_lds_dwordx4 v132, s[88:89]
	s_mov_b32 m0, s93
	s_add_i32 s94, s57, 0x6000
	global_load_lds_dwordx4 v128, s[8:9]
	s_mov_b32 m0, s94
	v_writelane_b32 v255, s76, 8
	global_load_lds_dwordx4 v132, s[8:9]
	v_mov_b32_e32 v131, v209
	v_mov_b32_e32 v135, v209
	v_mov_b32_e32 v129, v209
	v_mov_b32_e32 v133, v209
	v_writelane_b32 v255, s45, 9
	v_lshl_add_u64 v[6:7], s[90:91], 0, v[130:131]
	v_lshl_add_u64 v[4:5], s[90:91], 0, v[134:135]
	v_lshl_add_u64 v[2:3], s[88:89], 0, v[128:129]
	s_cmp_lg_u32 s7, 1
	v_lshl_add_u64 v[0:1], s[88:89], 0, v[132:133]
	s_cbranch_scc1 .LBB0_618
	s_barrier
	s_setprio 1

.LBB0_631:
	s_add_u32 s22, s88, 0xfff80080
	s_addc_u32 s23, s89, -1
	s_add_i32 s44, 0, 0x10000
	s_cmp_eq_u32 s43, 28
	s_cselect_b32 s23, s30, s23
	s_cselect_b32 s22, s31, s22
	s_cselect_b32 s91, s38, s42
	s_cselect_b32 s90, s39, s41
	s_add_i32 s81, 0, 0x14000
	v_add_u32_e32 v156, s44, v141
	v_add_u32_e32 v172, s81, v141
	ds_read_b128 v[144:147], v156
	ds_read_b128 v[148:151], v156 offset:1024
	ds_read_b128 v[152:155], v156 offset:2048
	ds_read_b128 v[156:159], v156 offset:3072
	ds_read_b128 v[160:163], v172
	ds_read_b128 v[164:167], v172 offset:1024
	ds_read_b128 v[168:171], v172 offset:2048
	ds_read_b128 v[172:175], v172 offset:3072
	v_lshl_add_u64 v[212:213], s[88:89], 0, v[136:137]
	s_add_i32 m0, s57, 0xc000
	ds_read_b128 v[176:179], v143
	ds_read_b128 v[180:183], v143 offset:1024
	ds_read_b128 v[184:187], v143 offset:2048
	ds_read_b128 v[188:191], v143 offset:3072
	ds_read_b128 v[192:195], v143 offset:4096
	ds_read_b128 v[196:199], v143 offset:5120
	ds_read_b128 v[200:203], v143 offset:6144
	ds_read_b128 v[204:207], v143 offset:7168
	global_load_lds_dwordx4 v[212:213], off
	v_lshl_add_u64 v[212:213], s[88:89], 0, v[138:139]
	s_add_i32 m0, s57, 0xe000
	s_nop 0
	global_load_lds_dwordx4 v[212:213], off
	s_waitcnt vmcnt(8)
	s_waitcnt lgkmcnt(0)
	s_barrier
	s_waitcnt lgkmcnt(0)
	v_mfma_f32_16x16x32_bf16 v[124:127], v[144:147], v[176:179], v[124:127]
	v_mfma_f32_16x16x32_bf16 v[120:123], v[152:155], v[176:179], v[120:123]
	v_mfma_f32_16x16x32_bf16 v[116:119], v[144:147], v[184:187], v[116:119]
	v_mfma_f32_16x16x32_bf16 v[112:115], v[152:155], v[184:187], v[112:115]
	v_mfma_f32_16x16x32_bf16 v[100:103], v[144:147], v[192:195], v[100:103]
	v_mfma_f32_16x16x32_bf16 v[96:99], v[152:155], v[192:195], v[96:99]
	v_mfma_f32_16x16x32_bf16 v[84:87], v[144:147], v[200:203], v[84:87]
	v_mfma_f32_16x16x32_bf16 v[80:83], v[152:155], v[200:203], v[80:83]
	v_mfma_f32_16x16x32_bf16 v[124:127], v[148:151], v[180:183], v[124:127]
	v_mfma_f32_16x16x32_bf16 v[120:123], v[156:159], v[180:183], v[120:123]
	v_mfma_f32_16x16x32_bf16 v[116:119], v[148:151], v[188:191], v[116:119]
	v_mfma_f32_16x16x32_bf16 v[112:115], v[156:159], v[188:191], v[112:115]
	v_mfma_f32_16x16x32_bf16 v[100:103], v[148:151], v[196:199], v[100:103]
	v_mfma_f32_16x16x32_bf16 v[96:99], v[156:159], v[196:199], v[96:99]
	v_mfma_f32_16x16x32_bf16 v[84:87], v[148:151], v[204:207], v[84:87]
	v_mfma_f32_16x16x32_bf16 v[80:83], v[156:159], v[204:207], v[80:83]
	v_mfma_f32_16x16x32_bf16 v[108:111], v[160:163], v[176:179], v[108:111]
	v_mfma_f32_16x16x32_bf16 v[104:107], v[168:171], v[176:179], v[104:107]
	v_mfma_f32_16x16x32_bf16 v[92:95], v[160:163], v[184:187], v[92:95]
	v_mfma_f32_16x16x32_bf16 v[88:91], v[168:171], v[184:187], v[88:91]
	v_mfma_f32_16x16x32_bf16 v[76:79], v[160:163], v[192:195], v[76:79]
	v_mfma_f32_16x16x32_bf16 v[72:75], v[168:171], v[192:195], v[72:75]
	v_mfma_f32_16x16x32_bf16 v[68:71], v[160:163], v[200:203], v[68:71]
	v_mfma_f32_16x16x32_bf16 v[64:67], v[168:171], v[200:203], v[64:67]
	v_mfma_f32_16x16x32_bf16 v[108:111], v[164:167], v[180:183], v[108:111]
	v_mfma_f32_16x16x32_bf16 v[104:107], v[172:175], v[180:183], v[104:107]
	v_mfma_f32_16x16x32_bf16 v[92:95], v[164:167], v[188:191], v[92:95]
	v_mfma_f32_16x16x32_bf16 v[88:91], v[172:175], v[188:191], v[88:91]
	v_mfma_f32_16x16x32_bf16 v[76:79], v[164:167], v[196:199], v[76:79]
	v_mfma_f32_16x16x32_bf16 v[72:75], v[172:175], v[196:199], v[72:75]
	v_mfma_f32_16x16x32_bf16 v[68:71], v[164:167], v[204:207], v[68:71]
	v_mfma_f32_16x16x32_bf16 v[64:67], v[172:175], v[204:207], v[64:67]
	s_barrier
	s_add_i32 s44, s44, s96
	v_lshl_add_u64 v[212:213], s[90:91], 0, v[130:131]
	s_mov_b32 m0, s44
	ds_read_b128 v[176:179], v143 offset:16384
	ds_read_b128 v[180:183], v143 offset:17408
	ds_read_b128 v[184:187], v143 offset:18432
	ds_read_b128 v[188:191], v143 offset:19456
	ds_read_b128 v[192:195], v143 offset:20480
	ds_read_b128 v[196:199], v143 offset:21504
	ds_read_b128 v[200:203], v143 offset:22528
	ds_read_b128 v[204:207], v143 offset:23552
	global_load_lds_dwordx4 v[212:213], off
	s_add_i32 m0, s44, 0x2000
	s_add_u32 s44, s90, 0x80000
	v_lshl_add_u64 v[214:215], s[90:91], 0, v[134:135]
	s_addc_u32 s45, s91, 0
	s_add_i32 s81, s81, s96
	global_load_lds_dwordx4 v[214:215], off
	v_lshl_add_u64 v[216:217], s[44:45], 0, v[130:131]
	s_mov_b32 m0, s81
	v_lshl_add_u64 v[218:219], s[22:23], 0, v[132:133]
	global_load_lds_dwordx4 v[216:217], off
	v_lshl_add_u64 v[216:217], s[44:45], 0, v[134:135]
	s_add_i32 m0, s81, 0x2000
	s_nop 0
	global_load_lds_dwordx4 v[216:217], off
	v_lshl_add_u64 v[216:217], s[22:23], 0, v[128:129]
	s_mov_b32 m0, s57
	s_nop 0
	global_load_lds_dwordx4 v[216:217], off
	s_mov_b32 m0, s97
	s_nop 0
	global_load_lds_dwordx4 v[218:219], off
	s_waitcnt vmcnt(8)
	s_waitcnt lgkmcnt(0)
	s_barrier
	s_waitcnt lgkmcnt(0)
	v_mfma_f32_16x16x32_bf16 v[60:63], v[144:147], v[176:179], v[60:63]
	v_mfma_f32_16x16x32_bf16 v[56:59], v[152:155], v[176:179], v[56:59]
	v_mfma_f32_16x16x32_bf16 v[52:55], v[144:147], v[184:187], v[52:55]
	v_mfma_f32_16x16x32_bf16 v[48:51], v[152:155], v[184:187], v[48:51]
	v_mfma_f32_16x16x32_bf16 v[36:39], v[144:147], v[192:195], v[36:39]
	v_mfma_f32_16x16x32_bf16 v[32:35], v[152:155], v[192:195], v[32:35]
	v_mfma_f32_16x16x32_bf16 v[20:23], v[144:147], v[200:203], v[20:23]
	v_mfma_f32_16x16x32_bf16 v[16:19], v[152:155], v[200:203], v[16:19]
	v_mfma_f32_16x16x32_bf16 v[60:63], v[148:151], v[180:183], v[60:63]
	v_mfma_f32_16x16x32_bf16 v[56:59], v[156:159], v[180:183], v[56:59]
	v_mfma_f32_16x16x32_bf16 v[52:55], v[148:151], v[188:191], v[52:55]
	v_mfma_f32_16x16x32_bf16 v[48:51], v[156:159], v[188:191], v[48:51]
	v_mfma_f32_16x16x32_bf16 v[36:39], v[148:151], v[196:199], v[36:39]
	v_mfma_f32_16x16x32_bf16 v[32:35], v[156:159], v[196:199], v[32:35]
	v_mfma_f32_16x16x32_bf16 v[20:23], v[148:151], v[204:207], v[20:23]
	v_mfma_f32_16x16x32_bf16 v[16:19], v[156:159], v[204:207], v[16:19]
	v_mfma_f32_16x16x32_bf16 v[44:47], v[160:163], v[176:179], v[44:47]
	v_mfma_f32_16x16x32_bf16 v[40:43], v[168:171], v[176:179], v[40:43]
	v_mfma_f32_16x16x32_bf16 v[28:31], v[160:163], v[184:187], v[28:31]
	v_mfma_f32_16x16x32_bf16 v[24:27], v[168:171], v[184:187], v[24:27]
	v_mfma_f32_16x16x32_bf16 v[12:15], v[160:163], v[192:195], v[12:15]
	v_mfma_f32_16x16x32_bf16 v[8:11], v[168:171], v[192:195], v[8:11]
	v_mfma_f32_16x16x32_bf16 v[4:7], v[160:163], v[200:203], v[4:7]
	v_mfma_f32_16x16x32_bf16 v[0:3], v[168:171], v[200:203], v[0:3]
	v_mfma_f32_16x16x32_bf16 v[44:47], v[164:167], v[180:183], v[44:47]
	v_mfma_f32_16x16x32_bf16 v[40:43], v[172:175], v[180:183], v[40:43]
	v_mfma_f32_16x16x32_bf16 v[28:31], v[164:167], v[188:191], v[28:31]
	v_mfma_f32_16x16x32_bf16 v[24:27], v[172:175], v[188:191], v[24:27]
	v_mfma_f32_16x16x32_bf16 v[12:15], v[164:167], v[196:199], v[12:15]
	v_mfma_f32_16x16x32_bf16 v[8:11], v[172:175], v[196:199], v[8:11]
	v_mfma_f32_16x16x32_bf16 v[4:7], v[164:167], v[204:207], v[4:7]
	v_mfma_f32_16x16x32_bf16 v[0:3], v[172:175], v[204:207], v[0:3]
	s_barrier
	s_add_i32 s44, 0, 0x18000
	s_add_i32 s45, 0, 0x1c000
	v_add_u32_e32 v156, s44, v141
	v_add_u32_e32 v172, s45, v141
	ds_read_b128 v[144:147], v156
	ds_read_b128 v[148:151], v156 offset:1024
	ds_read_b128 v[152:155], v156 offset:2048
	ds_read_b128 v[156:159], v156 offset:3072
	ds_read_b128 v[160:163], v172
	ds_read_b128 v[164:167], v172 offset:1024
	ds_read_b128 v[168:171], v172 offset:2048
	ds_read_b128 v[172:175], v172 offset:3072
	s_add_u32 s22, s22, 0x80000
	s_addc_u32 s23, s23, 0
	s_mov_b32 m0, s93
	v_lshl_add_u64 v[220:221], s[22:23], 0, v[128:129]
	ds_read_b128 v[176:179], v143 offset:32768
	ds_read_b128 v[180:183], v143 offset:33792
	ds_read_b128 v[184:187], v143 offset:34816
	ds_read_b128 v[188:191], v143 offset:35840
	ds_read_b128 v[192:195], v143 offset:36864
	ds_read_b128 v[196:199], v143 offset:37888
	ds_read_b128 v[200:203], v143 offset:38912
	ds_read_b128 v[204:207], v143 offset:39936
	global_load_lds_dwordx4 v[220:221], off
	v_lshl_add_u64 v[220:221], s[22:23], 0, v[132:133]
	s_mov_b32 m0, s94
	s_nop 0
	global_load_lds_dwordx4 v[220:221], off
	s_waitcnt vmcnt(8)
	s_waitcnt lgkmcnt(0)
	s_barrier
	s_waitcnt lgkmcnt(0)
	v_mfma_f32_16x16x32_bf16 v[124:127], v[144:147], v[176:179], v[124:127]
	v_mfma_f32_16x16x32_bf16 v[120:123], v[152:155], v[176:179], v[120:123]
	v_mfma_f32_16x16x32_bf16 v[116:119], v[144:147], v[184:187], v[116:119]
	v_mfma_f32_16x16x32_bf16 v[112:115], v[152:155], v[184:187], v[112:115]
	v_mfma_f32_16x16x32_bf16 v[100:103], v[144:147], v[192:195], v[100:103]
	v_mfma_f32_16x16x32_bf16 v[96:99], v[152:155], v[192:195], v[96:99]
	v_mfma_f32_16x16x32_bf16 v[84:87], v[144:147], v[200:203], v[84:87]
	v_mfma_f32_16x16x32_bf16 v[80:83], v[152:155], v[200:203], v[80:83]
	v_mfma_f32_16x16x32_bf16 v[124:127], v[148:151], v[180:183], v[124:127]
	v_mfma_f32_16x16x32_bf16 v[120:123], v[156:159], v[180:183], v[120:123]
	v_mfma_f32_16x16x32_bf16 v[116:119], v[148:151], v[188:191], v[116:119]
	v_mfma_f32_16x16x32_bf16 v[112:115], v[156:159], v[188:191], v[112:115]
	v_mfma_f32_16x16x32_bf16 v[100:103], v[148:151], v[196:199], v[100:103]
	v_mfma_f32_16x16x32_bf16 v[96:99], v[156:159], v[196:199], v[96:99]
	v_mfma_f32_16x16x32_bf16 v[84:87], v[148:151], v[204:207], v[84:87]
	v_mfma_f32_16x16x32_bf16 v[80:83], v[156:159], v[204:207], v[80:83]
	v_mfma_f32_16x16x32_bf16 v[108:111], v[160:163], v[176:179], v[108:111]
	v_mfma_f32_16x16x32_bf16 v[104:107], v[168:171], v[176:179], v[104:107]
	v_mfma_f32_16x16x32_bf16 v[92:95], v[160:163], v[184:187], v[92:95]
	v_mfma_f32_16x16x32_bf16 v[88:91], v[168:171], v[184:187], v[88:91]
	v_mfma_f32_16x16x32_bf16 v[76:79], v[160:163], v[192:195], v[76:79]
	v_mfma_f32_16x16x32_bf16 v[72:75], v[168:171], v[192:195], v[72:75]
	v_mfma_f32_16x16x32_bf16 v[68:71], v[160:163], v[200:203], v[68:71]
	v_mfma_f32_16x16x32_bf16 v[64:67], v[168:171], v[200:203], v[64:67]
	v_mfma_f32_16x16x32_bf16 v[108:111], v[164:167], v[180:183], v[108:111]
	v_mfma_f32_16x16x32_bf16 v[104:107], v[172:175], v[180:183], v[104:107]
	v_mfma_f32_16x16x32_bf16 v[92:95], v[164:167], v[188:191], v[92:95]
	v_mfma_f32_16x16x32_bf16 v[88:91], v[172:175], v[188:191], v[88:91]
	v_mfma_f32_16x16x32_bf16 v[76:79], v[164:167], v[196:199], v[76:79]
	v_mfma_f32_16x16x32_bf16 v[72:75], v[172:175], v[196:199], v[72:75]
	v_mfma_f32_16x16x32_bf16 v[68:71], v[164:167], v[204:207], v[68:71]
	v_mfma_f32_16x16x32_bf16 v[64:67], v[172:175], v[204:207], v[64:67]
	s_barrier
	s_add_i32 s22, s44, s96
	v_lshl_add_u64 v[212:213], v[212:213], 0, s[54:55]
	s_mov_b32 m0, s22
	ds_read_b128 v[176:179], v143 offset:49152
	ds_read_b128 v[180:183], v143 offset:50176
	ds_read_b128 v[184:187], v143 offset:51200
	ds_read_b128 v[188:191], v143 offset:52224
	ds_read_b128 v[192:195], v143 offset:53248
	ds_read_b128 v[196:199], v143 offset:54272
	ds_read_b128 v[200:203], v143 offset:55296
	ds_read_b128 v[204:207], v143 offset:56320
	global_load_lds_dwordx4 v[212:213], off
	s_add_i32 m0, s22, 0x2000
	s_add_u32 s22, s90, 0x80080
	v_lshl_add_u64 v[212:213], v[214:215], 0, s[54:55]
	s_addc_u32 s23, s91, 0
	s_add_i32 s44, s45, s96
	global_load_lds_dwordx4 v[212:213], off
	v_lshl_add_u64 v[212:213], s[22:23], 0, v[130:131]
	s_mov_b32 m0, s44
	s_nop 0
	global_load_lds_dwordx4 v[212:213], off
	v_lshl_add_u64 v[212:213], s[22:23], 0, v[134:135]
	s_add_i32 m0, s44, 0x2000
	s_nop 0
	global_load_lds_dwordx4 v[212:213], off
	v_lshl_add_u64 v[212:213], v[216:217], 0, s[54:55]
	s_mov_b32 m0, s92
	s_nop 0
	global_load_lds_dwordx4 v[212:213], off
	v_lshl_add_u64 v[212:213], v[218:219], 0, s[54:55]
	s_mov_b32 m0, s6
	s_nop 0
	global_load_lds_dwordx4 v[212:213], off
	s_waitcnt vmcnt(8)
	s_waitcnt lgkmcnt(0)
	s_barrier
	s_waitcnt lgkmcnt(0)
	v_mfma_f32_16x16x32_bf16 v[60:63], v[144:147], v[176:179], v[60:63]
	v_mfma_f32_16x16x32_bf16 v[56:59], v[152:155], v[176:179], v[56:59]
	v_mfma_f32_16x16x32_bf16 v[52:55], v[144:147], v[184:187], v[52:55]
	v_mfma_f32_16x16x32_bf16 v[48:51], v[152:155], v[184:187], v[48:51]
	v_mfma_f32_16x16x32_bf16 v[36:39], v[144:147], v[192:195], v[36:39]
	v_mfma_f32_16x16x32_bf16 v[32:35], v[152:155], v[192:195], v[32:35]
	v_mfma_f32_16x16x32_bf16 v[20:23], v[144:147], v[200:203], v[20:23]
	v_mfma_f32_16x16x32_bf16 v[16:19], v[152:155], v[200:203], v[16:19]
	v_mfma_f32_16x16x32_bf16 v[60:63], v[148:151], v[180:183], v[60:63]
	v_mfma_f32_16x16x32_bf16 v[56:59], v[156:159], v[180:183], v[56:59]
	v_mfma_f32_16x16x32_bf16 v[52:55], v[148:151], v[188:191], v[52:55]
	v_mfma_f32_16x16x32_bf16 v[48:51], v[156:159], v[188:191], v[48:51]
	v_mfma_f32_16x16x32_bf16 v[36:39], v[148:151], v[196:199], v[36:39]
	v_mfma_f32_16x16x32_bf16 v[32:35], v[156:159], v[196:199], v[32:35]
	v_mfma_f32_16x16x32_bf16 v[20:23], v[148:151], v[204:207], v[20:23]
	v_mfma_f32_16x16x32_bf16 v[16:19], v[156:159], v[204:207], v[16:19]
	v_mfma_f32_16x16x32_bf16 v[44:47], v[160:163], v[176:179], v[44:47]
	v_mfma_f32_16x16x32_bf16 v[40:43], v[168:171], v[176:179], v[40:43]
	v_mfma_f32_16x16x32_bf16 v[28:31], v[160:163], v[184:187], v[28:31]
	v_mfma_f32_16x16x32_bf16 v[24:27], v[168:171], v[184:187], v[24:27]
	v_mfma_f32_16x16x32_bf16 v[12:15], v[160:163], v[192:195], v[12:15]
	v_mfma_f32_16x16x32_bf16 v[8:11], v[168:171], v[192:195], v[8:11]
	v_mfma_f32_16x16x32_bf16 v[4:7], v[160:163], v[200:203], v[4:7]
	v_mfma_f32_16x16x32_bf16 v[0:3], v[168:171], v[200:203], v[0:3]
	v_mfma_f32_16x16x32_bf16 v[44:47], v[164:167], v[180:183], v[44:47]
	v_mfma_f32_16x16x32_bf16 v[40:43], v[172:175], v[180:183], v[40:43]
	v_mfma_f32_16x16x32_bf16 v[28:31], v[164:167], v[188:191], v[28:31]
	v_mfma_f32_16x16x32_bf16 v[24:27], v[172:175], v[188:191], v[24:27]
	v_mfma_f32_16x16x32_bf16 v[12:15], v[164:167], v[196:199], v[12:15]
	v_mfma_f32_16x16x32_bf16 v[8:11], v[172:175], v[196:199], v[8:11]
	v_mfma_f32_16x16x32_bf16 v[4:7], v[164:167], v[204:207], v[4:7]
	v_mfma_f32_16x16x32_bf16 v[0:3], v[172:175], v[204:207], v[0:3]
	s_barrier
	s_add_i32 s43, s43, 2
	s_add_u32 s88, s88, 0x100
	s_addc_u32 s89, s89, 0
	s_add_u32 s41, s41, 0x100
	s_addc_u32 s42, s42, 0
	s_cmp_gt_u32 s43, 29
	s_cbranch_scc0 .LBB0_631
	s_cmp_eq_u32 s40, 0
	s_cselect_b64 s[30:31], -1, 0
	s_cmp_lg_u32 s40, 0
	s_mov_b64 s[38:39], -1
	s_cbranch_scc0 .LBB0_634
	s_lshl_b32 s22, s80, 8
	s_or_b32 s22, s22, s53
	s_ashr_i32 s22, s22, 6
	s_mov_b64 s[38:39], 0

.LBB0_636:
	s_setprio 0
	s_waitcnt vmcnt(0)
	s_cmpk_gt_u32 s46, 0xff
	s_cbranch_scc1 .LBB0_638
	s_barrier

.LBB0_1246:
	s_or_b64 exec, exec, s[8:9]
	v_mov_b32_e32 v246, v226
	s_waitcnt vmcnt(0) lgkmcnt(0)
	s_barrier
	s_and_b64 vcc, exec, s[4:5]
	v_readfirstlane_b32 s6, v246
	s_cbranch_vccnz .LBB0_1335
	v_lshlrev_b32_e32 v4, 4, v246
	v_add_u32_e32 v1, 0x2000, v4
	v_ashrrev_i32_e32 v0, 31, v1
	v_lshrrev_b32_e32 v0, 22, v0
	v_add_u32_e32 v0, v1, v0
	v_ashrrev_i32_e32 v0, 10, v0
	v_lshlrev_b32_e32 v2, 5, v0
	v_and_b32_e32 v3, 32, v2
	v_mul_i32_i24_e32 v2, 0x400, v0
	v_sub_u32_e32 v1, v1, v2
	v_lshrrev_b32_e32 v2, 4, v1
	v_bitop3_b32 v2, v2, v1, 32 bitop3:0x6c
	v_ashrrev_i32_e32 v1, 31, v2
	v_lshrrev_b32_e32 v1, 26, v1
	v_add_u32_e32 v5, v2, v1
	v_ashrrev_i32_e32 v1, 6, v5
	v_and_b32_e32 v5, 0xc0, v5
	v_sub_u32_e32 v2, v2, v5
	v_ashrrev_i16_sdwa v2, v230, sext(v2) dst_sel:DWORD dst_unused:UNUSED_PAD src0_sel:DWORD src1_sel:BYTE_0
	v_lshlrev_b32_e32 v5, 3, v0
	v_bfe_i32 v2, v2, 0, 16
	v_and_b32_e32 v5, 0xffff0, v5
	v_add_u32_e32 v3, v3, v2
	v_add_lshl_u32 v5, v1, v5, 12
	v_lshl_add_u32 v128, v3, 1, v5
	v_ashrrev_i32_e32 v3, 31, v246
	v_lshrrev_b32_e32 v3, 26, v3
	v_add_u32_e32 v3, v246, v3
	v_ashrrev_i32_e32 v3, 6, v3
	v_lshlrev_b32_e32 v5, 5, v3
	s_mov_b32 s87, s27
	v_and_b32_e32 v6, 32, v5
	v_bfe_i32 v5, v246, 27, 1
	s_lshl_b64 s[4:5], s[86:87], 23
	v_lshrrev_b32_e32 v5, 22, v5
	s_add_u32 s38, s14, 0x12800000
	v_add_u32_e32 v5, v4, v5
	s_addc_u32 s39, s15, 0
	v_and_b32_e32 v5, 0xfffffc00, v5
	s_add_u32 s4, s14, s4
	v_sub_u32_e32 v4, v4, v5
	v_writelane_b32 v255, s14, 4
	s_addc_u32 s5, s15, s5
	v_lshrrev_b32_e32 v5, 4, v4
	s_add_u32 s40, s4, 0x7400000
	v_bitop3_b32 v5, v5, v4, 32 bitop3:0x6c
	v_writelane_b32 v255, s15, 5
	s_addc_u32 s41, s5, 0
	v_ashrrev_i32_e32 v4, 31, v5
	v_writelane_b32 v255, s86, 6
	s_cmp_eq_u32 s86, 0
	v_lshrrev_b32_e32 v4, 26, v4
	s_cselect_b32 s4, 0, 0x50
	v_add_u32_e32 v7, v5, v4
	s_add_u32 s4, s50, s4
	v_ashrrev_i32_e32 v4, 6, v7
	v_and_b32_e32 v7, 0xc0, v7
	v_writelane_b32 v254, s47, 58
	s_addc_u32 s5, s51, 0
	s_ashr_i32 s7, s6, 6
	v_sub_u32_e32 v5, v5, v7
	s_ashr_i32 s31, s6, 8
	s_lshl_b32 s43, s7, 10
	v_ashrrev_i16_sdwa v5, v230, sext(v5) dst_sel:DWORD dst_unused:UNUSED_PAD src0_sel:DWORD src1_sel:BYTE_0
	v_lshlrev_b32_e32 v7, 3, v3
	v_readlane_b32 s8, v254, 31
	v_bfe_i32 v5, v5, 0, 16
	v_and_b32_e32 v7, 0xffff0, v7
	v_readlane_b32 s9, v254, 32
	s_add_u32 s96, s40, s8
	v_add_u32_e32 v6, v6, v5
	v_add_lshl_u32 v7, v4, v7, 12
	s_addc_u32 s97, s41, s9
	s_add_i32 s45, s43, 0
	v_lshl_add_u32 v208, v6, 1, v7
	s_add_i32 m0, s45, 0x10000
	s_load_dwordx2 s[4:5], s[4:5], 0x0
	global_load_lds_dwordx4 v208, s[96:97]
	s_add_i32 m0, s45, 0x12000
	s_add_u32 s8, s96, 0x80000
	global_load_lds_dwordx4 v128, s[96:97]
	s_addc_u32 s9, s97, 0
	s_add_i32 m0, s45, 0x14000
	s_load_dwordx4 s[12:15], s[50:51], 0x18
	global_load_lds_dwordx4 v208, s[8:9]
	s_add_i32 m0, s45, 0x16000
	v_writelane_b32 v255, s87, 7
	global_load_lds_dwordx4 v128, s[8:9]
	v_readlane_b32 s8, v254, 29
	v_readlane_b32 s9, v254, 30
	s_add_u32 s92, s38, s8
	s_addc_u32 s93, s39, s9
	s_add_i32 s52, s45, 0x2000
	s_mov_b32 m0, s45
	s_add_u32 s8, s92, 0x80000
	global_load_lds_dwordx4 v208, s[92:93]
	s_mov_b32 m0, s52
	s_addc_u32 s9, s93, 0
	s_add_i32 s53, s45, 0x4000
	global_load_lds_dwordx4 v128, s[92:93]
	s_mov_b32 m0, s53
	s_add_i32 s85, s45, 0x6000
	global_load_lds_dwordx4 v208, s[8:9]
	s_mov_b32 m0, s85
	s_waitcnt lgkmcnt(0)
	v_writelane_b32 v254, s4, 60
	global_load_lds_dwordx4 v128, s[8:9]
	s_nop 0
	v_writelane_b32 v254, s5, 61
	s_load_dwordx2 s[4:5], s[50:51], 0x50
	v_writelane_b32 v255, s12, 0
	s_cmp_eq_u32 s31, 1
	s_cselect_b64 s[50:51], -1, 0
	v_writelane_b32 v255, s13, 1
	v_writelane_b32 v255, s14, 2
	s_waitcnt lgkmcnt(0)
	v_writelane_b32 v254, s4, 62
	v_writelane_b32 v255, s15, 3
	s_cmp_lg_u32 s31, 1
	v_writelane_b32 v254, s5, 63
	s_cbranch_scc1 .LBB0_1249
	s_barrier
	s_setprio 1

.LBB0_1259:
	s_add_u32 s22, s92, s76
	s_addc_u32 s23, s93, s77
	s_add_u32 s80, s96, s76
	s_addc_u32 s81, s97, s77
	s_cmp_eq_u32 s44, 0
	s_cselect_b32 s23, s15, s23
	s_cselect_b32 s22, s91, s22
	s_cselect_b32 vcc_hi, s89, s81
	s_cselect_b32 vcc_lo, s8, s80
	s_add_i32 s80, 0, 0x10000
	v_add_u32_e32 v141, s80, v138
	s_add_i32 s83, 0, 0x14000
	ds_read_b128 v[142:145], v141
	ds_read_b128 v[146:149], v141 offset:1024
	ds_read_b128 v[150:153], v141 offset:2048
	ds_read_b128 v[154:157], v141 offset:3072
	v_add_u32_e32 v141, s83, v138
	ds_read_b128 v[158:161], v141
	ds_read_b128 v[162:165], v141 offset:1024
	ds_read_b128 v[166:169], v141 offset:2048
	ds_read_b128 v[170:173], v141 offset:3072
	v_lshl_add_u64 v[206:207], s[92:93], 0, v[136:137]
	s_add_i32 m0, s45, 0xc000
	ds_read_b128 v[174:177], v140
	ds_read_b128 v[178:181], v140 offset:1024
	ds_read_b128 v[182:185], v140 offset:2048
	ds_read_b128 v[186:189], v140 offset:3072
	ds_read_b128 v[190:193], v140 offset:4096
	ds_read_b128 v[194:197], v140 offset:5120
	ds_read_b128 v[198:201], v140 offset:6144
	ds_read_b128 v[202:205], v140 offset:7168
	global_load_lds_dwordx4 v[206:207], off
	v_lshl_add_u64 v[206:207], s[92:93], 0, v[134:135]
	s_add_i32 m0, s45, 0xe000
	s_nop 0
	global_load_lds_dwordx4 v[206:207], off
	s_waitcnt vmcnt(8)
	s_waitcnt lgkmcnt(0)
	s_barrier
	s_waitcnt lgkmcnt(0)
	v_mfma_f32_16x16x32_bf16 v[124:127], v[142:145], v[174:177], v[124:127]
	v_mfma_f32_16x16x32_bf16 v[120:123], v[150:153], v[174:177], v[120:123]
	v_mfma_f32_16x16x32_bf16 v[108:111], v[142:145], v[182:185], v[108:111]
	v_mfma_f32_16x16x32_bf16 v[104:107], v[150:153], v[182:185], v[104:107]
	v_mfma_f32_16x16x32_bf16 v[92:95], v[142:145], v[190:193], v[92:95]
	v_mfma_f32_16x16x32_bf16 v[88:91], v[150:153], v[190:193], v[88:91]
	v_mfma_f32_16x16x32_bf16 v[76:79], v[142:145], v[198:201], v[76:79]
	v_mfma_f32_16x16x32_bf16 v[72:75], v[150:153], v[198:201], v[72:75]
	v_mfma_f32_16x16x32_bf16 v[124:127], v[146:149], v[178:181], v[124:127]
	v_mfma_f32_16x16x32_bf16 v[120:123], v[154:157], v[178:181], v[120:123]
	v_mfma_f32_16x16x32_bf16 v[108:111], v[146:149], v[186:189], v[108:111]
	v_mfma_f32_16x16x32_bf16 v[104:107], v[154:157], v[186:189], v[104:107]
	v_mfma_f32_16x16x32_bf16 v[92:95], v[146:149], v[194:197], v[92:95]
	v_mfma_f32_16x16x32_bf16 v[88:91], v[154:157], v[194:197], v[88:91]
	v_mfma_f32_16x16x32_bf16 v[76:79], v[146:149], v[202:205], v[76:79]
	v_mfma_f32_16x16x32_bf16 v[72:75], v[154:157], v[202:205], v[72:75]
	v_mfma_f32_16x16x32_bf16 v[116:119], v[158:161], v[174:177], v[116:119]
	v_mfma_f32_16x16x32_bf16 v[112:115], v[166:169], v[174:177], v[112:115]
	v_mfma_f32_16x16x32_bf16 v[100:103], v[158:161], v[182:185], v[100:103]
	v_mfma_f32_16x16x32_bf16 v[96:99], v[166:169], v[182:185], v[96:99]
	v_mfma_f32_16x16x32_bf16 v[84:87], v[158:161], v[190:193], v[84:87]
	v_mfma_f32_16x16x32_bf16 v[80:83], v[166:169], v[190:193], v[80:83]
	v_mfma_f32_16x16x32_bf16 v[68:71], v[158:161], v[198:201], v[68:71]
	v_mfma_f32_16x16x32_bf16 v[64:67], v[166:169], v[198:201], v[64:67]
	v_mfma_f32_16x16x32_bf16 v[116:119], v[162:165], v[178:181], v[116:119]
	v_mfma_f32_16x16x32_bf16 v[112:115], v[170:173], v[178:181], v[112:115]
	v_mfma_f32_16x16x32_bf16 v[100:103], v[162:165], v[186:189], v[100:103]
	v_mfma_f32_16x16x32_bf16 v[96:99], v[170:173], v[186:189], v[96:99]
	v_mfma_f32_16x16x32_bf16 v[84:87], v[162:165], v[194:197], v[84:87]
	v_mfma_f32_16x16x32_bf16 v[80:83], v[170:173], v[194:197], v[80:83]
	v_mfma_f32_16x16x32_bf16 v[68:71], v[162:165], v[202:205], v[68:71]
	v_mfma_f32_16x16x32_bf16 v[64:67], v[170:173], v[202:205], v[64:67]
	s_barrier
	s_add_i32 s80, s80, s43
	v_lshl_add_u64 v[206:207], vcc, 0, v[208:209]
	s_mov_b32 m0, s80
	ds_read_b128 v[174:177], v140 offset:16384
	ds_read_b128 v[178:181], v140 offset:17408
	ds_read_b128 v[182:185], v140 offset:18432
	ds_read_b128 v[186:189], v140 offset:19456
	ds_read_b128 v[190:193], v140 offset:20480
	ds_read_b128 v[194:197], v140 offset:21504
	ds_read_b128 v[198:201], v140 offset:22528
	ds_read_b128 v[202:205], v140 offset:23552
	global_load_lds_dwordx4 v[206:207], off
	s_add_i32 m0, s80, 0x2000
	s_add_u32 s80, vcc_lo, 0x80000
	v_lshl_add_u64 v[212:213], vcc, 0, v[128:129]
	s_addc_u32 s81, vcc_hi, 0
	s_add_i32 s83, s83, s43
	global_load_lds_dwordx4 v[212:213], off
	v_lshl_add_u64 v[216:217], s[80:81], 0, v[208:209]
	s_mov_b32 m0, s83
	v_lshl_add_u64 v[218:219], s[22:23], 0, v[128:129]
	global_load_lds_dwordx4 v[216:217], off
	v_lshl_add_u64 v[216:217], s[80:81], 0, v[128:129]
	s_add_i32 m0, s83, 0x2000
	s_nop 0
	global_load_lds_dwordx4 v[216:217], off
	v_lshl_add_u64 v[216:217], s[22:23], 0, v[208:209]
	s_mov_b32 m0, s45
	s_nop 0
	global_load_lds_dwordx4 v[216:217], off
	s_mov_b32 m0, s52
	s_nop 0
	global_load_lds_dwordx4 v[218:219], off
	s_waitcnt vmcnt(8)
	s_waitcnt lgkmcnt(0)
	s_barrier
	s_waitcnt lgkmcnt(0)
	v_mfma_f32_16x16x32_bf16 v[60:63], v[142:145], v[174:177], v[60:63]
	v_mfma_f32_16x16x32_bf16 v[56:59], v[150:153], v[174:177], v[56:59]
	v_mfma_f32_16x16x32_bf16 v[44:47], v[142:145], v[182:185], v[44:47]
	v_mfma_f32_16x16x32_bf16 v[40:43], v[150:153], v[182:185], v[40:43]
	v_mfma_f32_16x16x32_bf16 v[28:31], v[142:145], v[190:193], v[28:31]
	v_mfma_f32_16x16x32_bf16 v[24:27], v[150:153], v[190:193], v[24:27]
	v_mfma_f32_16x16x32_bf16 v[12:15], v[142:145], v[198:201], v[12:15]
	v_mfma_f32_16x16x32_bf16 v[8:11], v[150:153], v[198:201], v[8:11]
	v_mfma_f32_16x16x32_bf16 v[60:63], v[146:149], v[178:181], v[60:63]
	v_mfma_f32_16x16x32_bf16 v[56:59], v[154:157], v[178:181], v[56:59]
	v_mfma_f32_16x16x32_bf16 v[44:47], v[146:149], v[186:189], v[44:47]
	v_mfma_f32_16x16x32_bf16 v[40:43], v[154:157], v[186:189], v[40:43]
	v_mfma_f32_16x16x32_bf16 v[28:31], v[146:149], v[194:197], v[28:31]
	v_mfma_f32_16x16x32_bf16 v[24:27], v[154:157], v[194:197], v[24:27]
	v_mfma_f32_16x16x32_bf16 v[12:15], v[146:149], v[202:205], v[12:15]
	v_mfma_f32_16x16x32_bf16 v[8:11], v[154:157], v[202:205], v[8:11]
	v_mfma_f32_16x16x32_bf16 v[52:55], v[158:161], v[174:177], v[52:55]
	v_mfma_f32_16x16x32_bf16 v[48:51], v[166:169], v[174:177], v[48:51]
	v_mfma_f32_16x16x32_bf16 v[36:39], v[158:161], v[182:185], v[36:39]
	v_mfma_f32_16x16x32_bf16 v[32:35], v[166:169], v[182:185], v[32:35]
	v_mfma_f32_16x16x32_bf16 v[20:23], v[158:161], v[190:193], v[20:23]
	v_mfma_f32_16x16x32_bf16 v[16:19], v[166:169], v[190:193], v[16:19]
	v_mfma_f32_16x16x32_bf16 v[4:7], v[158:161], v[198:201], v[4:7]
	v_mfma_f32_16x16x32_bf16 v[0:3], v[166:169], v[198:201], v[0:3]
	v_mfma_f32_16x16x32_bf16 v[52:55], v[162:165], v[178:181], v[52:55]
	v_mfma_f32_16x16x32_bf16 v[48:51], v[170:173], v[178:181], v[48:51]
	v_mfma_f32_16x16x32_bf16 v[36:39], v[162:165], v[186:189], v[36:39]
	v_mfma_f32_16x16x32_bf16 v[32:35], v[170:173], v[186:189], v[32:35]
	v_mfma_f32_16x16x32_bf16 v[20:23], v[162:165], v[194:197], v[20:23]
	v_mfma_f32_16x16x32_bf16 v[16:19], v[170:173], v[194:197], v[16:19]
	v_mfma_f32_16x16x32_bf16 v[4:7], v[162:165], v[202:205], v[4:7]
	v_mfma_f32_16x16x32_bf16 v[0:3], v[170:173], v[202:205], v[0:3]
	s_barrier
	s_add_i32 s80, 0, 0x18000
	v_add_u32_e32 v141, s80, v138
	s_add_i32 s81, 0, 0x1c000
	ds_read_b128 v[142:145], v141
	ds_read_b128 v[146:149], v141 offset:1024
	ds_read_b128 v[150:153], v141 offset:2048
	ds_read_b128 v[154:157], v141 offset:3072
	v_add_u32_e32 v141, s81, v138
	ds_read_b128 v[158:161], v141
	ds_read_b128 v[162:165], v141 offset:1024
	ds_read_b128 v[166:169], v141 offset:2048
	ds_read_b128 v[170:173], v141 offset:3072
	s_add_u32 s22, s22, 0x80000
	s_addc_u32 s23, s23, 0
	s_mov_b32 m0, s53
	v_lshl_add_u64 v[220:221], s[22:23], 0, v[208:209]
	ds_read_b128 v[174:177], v140 offset:32768
	ds_read_b128 v[178:181], v140 offset:33792
	ds_read_b128 v[182:185], v140 offset:34816
	ds_read_b128 v[186:189], v140 offset:35840
	ds_read_b128 v[190:193], v140 offset:36864
	ds_read_b128 v[194:197], v140 offset:37888
	ds_read_b128 v[198:201], v140 offset:38912
	ds_read_b128 v[202:205], v140 offset:39936
	global_load_lds_dwordx4 v[220:221], off
	v_lshl_add_u64 v[220:221], s[22:23], 0, v[128:129]
	s_mov_b32 m0, s85
	s_nop 0
	global_load_lds_dwordx4 v[220:221], off
	s_waitcnt vmcnt(8)
	s_waitcnt lgkmcnt(0)
	s_barrier
	s_waitcnt lgkmcnt(0)
	v_mfma_f32_16x16x32_bf16 v[124:127], v[142:145], v[174:177], v[124:127]
	v_mfma_f32_16x16x32_bf16 v[120:123], v[150:153], v[174:177], v[120:123]
	v_mfma_f32_16x16x32_bf16 v[108:111], v[142:145], v[182:185], v[108:111]
	v_mfma_f32_16x16x32_bf16 v[104:107], v[150:153], v[182:185], v[104:107]
	v_mfma_f32_16x16x32_bf16 v[92:95], v[142:145], v[190:193], v[92:95]
	v_mfma_f32_16x16x32_bf16 v[88:91], v[150:153], v[190:193], v[88:91]
	v_mfma_f32_16x16x32_bf16 v[76:79], v[142:145], v[198:201], v[76:79]
	v_mfma_f32_16x16x32_bf16 v[72:75], v[150:153], v[198:201], v[72:75]
	v_mfma_f32_16x16x32_bf16 v[124:127], v[146:149], v[178:181], v[124:127]
	v_mfma_f32_16x16x32_bf16 v[120:123], v[154:157], v[178:181], v[120:123]
	v_mfma_f32_16x16x32_bf16 v[108:111], v[146:149], v[186:189], v[108:111]
	v_mfma_f32_16x16x32_bf16 v[104:107], v[154:157], v[186:189], v[104:107]
	v_mfma_f32_16x16x32_bf16 v[92:95], v[146:149], v[194:197], v[92:95]
	v_mfma_f32_16x16x32_bf16 v[88:91], v[154:157], v[194:197], v[88:91]
	v_mfma_f32_16x16x32_bf16 v[76:79], v[146:149], v[202:205], v[76:79]
	v_mfma_f32_16x16x32_bf16 v[72:75], v[154:157], v[202:205], v[72:75]
	v_mfma_f32_16x16x32_bf16 v[116:119], v[158:161], v[174:177], v[116:119]
	v_mfma_f32_16x16x32_bf16 v[112:115], v[166:169], v[174:177], v[112:115]
	v_mfma_f32_16x16x32_bf16 v[100:103], v[158:161], v[182:185], v[100:103]
	v_mfma_f32_16x16x32_bf16 v[96:99], v[166:169], v[182:185], v[96:99]
	v_mfma_f32_16x16x32_bf16 v[84:87], v[158:161], v[190:193], v[84:87]
	v_mfma_f32_16x16x32_bf16 v[80:83], v[166:169], v[190:193], v[80:83]
	v_mfma_f32_16x16x32_bf16 v[68:71], v[158:161], v[198:201], v[68:71]
	v_mfma_f32_16x16x32_bf16 v[64:67], v[166:169], v[198:201], v[64:67]
	v_mfma_f32_16x16x32_bf16 v[116:119], v[162:165], v[178:181], v[116:119]
	v_mfma_f32_16x16x32_bf16 v[112:115], v[170:173], v[178:181], v[112:115]
	v_mfma_f32_16x16x32_bf16 v[100:103], v[162:165], v[186:189], v[100:103]
	v_mfma_f32_16x16x32_bf16 v[96:99], v[170:173], v[186:189], v[96:99]
	v_mfma_f32_16x16x32_bf16 v[84:87], v[162:165], v[194:197], v[84:87]
	v_mfma_f32_16x16x32_bf16 v[80:83], v[170:173], v[194:197], v[80:83]
	v_mfma_f32_16x16x32_bf16 v[68:71], v[162:165], v[202:205], v[68:71]
	v_mfma_f32_16x16x32_bf16 v[64:67], v[170:173], v[202:205], v[64:67]
	s_barrier
	s_add_i32 s22, s80, s43
	v_lshl_add_u64 v[206:207], v[206:207], 0, s[54:55]
	s_mov_b32 m0, s22
	ds_read_b128 v[174:177], v140 offset:49152
	ds_read_b128 v[178:181], v140 offset:50176
	ds_read_b128 v[182:185], v140 offset:51200
	ds_read_b128 v[186:189], v140 offset:52224
	ds_read_b128 v[190:193], v140 offset:53248
	ds_read_b128 v[194:197], v140 offset:54272
	ds_read_b128 v[198:201], v140 offset:55296
	ds_read_b128 v[202:205], v140 offset:56320
	global_load_lds_dwordx4 v[206:207], off
	s_add_i32 m0, s22, 0x2000
	s_add_u32 s22, vcc_lo, 0x80080
	v_lshl_add_u64 v[206:207], v[212:213], 0, s[54:55]
	s_addc_u32 s23, vcc_hi, 0
	s_add_i32 s80, s81, s43
	global_load_lds_dwordx4 v[206:207], off
	v_lshl_add_u64 v[206:207], s[22:23], 0, v[208:209]
	s_mov_b32 m0, s80
	s_nop 0
	global_load_lds_dwordx4 v[206:207], off
	v_lshl_add_u64 v[206:207], s[22:23], 0, v[128:129]
	s_add_i32 m0, s80, 0x2000
	s_nop 0
	global_load_lds_dwordx4 v[206:207], off
	v_lshl_add_u64 v[206:207], v[216:217], 0, s[54:55]
	s_mov_b32 m0, s9
	s_nop 0
	global_load_lds_dwordx4 v[206:207], off
	v_lshl_add_u64 v[206:207], v[218:219], 0, s[54:55]
	s_mov_b32 m0, s12
	s_nop 0
	global_load_lds_dwordx4 v[206:207], off
	s_waitcnt vmcnt(8)
	s_waitcnt lgkmcnt(0)
	s_barrier
	s_waitcnt lgkmcnt(0)
	v_mfma_f32_16x16x32_bf16 v[60:63], v[142:145], v[174:177], v[60:63]
	v_mfma_f32_16x16x32_bf16 v[56:59], v[150:153], v[174:177], v[56:59]
	v_mfma_f32_16x16x32_bf16 v[44:47], v[142:145], v[182:185], v[44:47]
	v_mfma_f32_16x16x32_bf16 v[40:43], v[150:153], v[182:185], v[40:43]
	v_mfma_f32_16x16x32_bf16 v[28:31], v[142:145], v[190:193], v[28:31]
	v_mfma_f32_16x16x32_bf16 v[24:27], v[150:153], v[190:193], v[24:27]
	v_mfma_f32_16x16x32_bf16 v[12:15], v[142:145], v[198:201], v[12:15]
	v_mfma_f32_16x16x32_bf16 v[8:11], v[150:153], v[198:201], v[8:11]
	v_mfma_f32_16x16x32_bf16 v[60:63], v[146:149], v[178:181], v[60:63]
	v_mfma_f32_16x16x32_bf16 v[56:59], v[154:157], v[178:181], v[56:59]
	v_mfma_f32_16x16x32_bf16 v[44:47], v[146:149], v[186:189], v[44:47]
	v_mfma_f32_16x16x32_bf16 v[40:43], v[154:157], v[186:189], v[40:43]
	v_mfma_f32_16x16x32_bf16 v[28:31], v[146:149], v[194:197], v[28:31]
	v_mfma_f32_16x16x32_bf16 v[24:27], v[154:157], v[194:197], v[24:27]
	v_mfma_f32_16x16x32_bf16 v[12:15], v[146:149], v[202:205], v[12:15]
	v_mfma_f32_16x16x32_bf16 v[8:11], v[154:157], v[202:205], v[8:11]
	v_mfma_f32_16x16x32_bf16 v[52:55], v[158:161], v[174:177], v[52:55]
	v_mfma_f32_16x16x32_bf16 v[48:51], v[166:169], v[174:177], v[48:51]
	v_mfma_f32_16x16x32_bf16 v[36:39], v[158:161], v[182:185], v[36:39]
	v_mfma_f32_16x16x32_bf16 v[32:35], v[166:169], v[182:185], v[32:35]
	v_mfma_f32_16x16x32_bf16 v[20:23], v[158:161], v[190:193], v[20:23]
	v_mfma_f32_16x16x32_bf16 v[16:19], v[166:169], v[190:193], v[16:19]
	v_mfma_f32_16x16x32_bf16 v[4:7], v[158:161], v[198:201], v[4:7]
	v_mfma_f32_16x16x32_bf16 v[0:3], v[166:169], v[198:201], v[0:3]
	v_mfma_f32_16x16x32_bf16 v[52:55], v[162:165], v[178:181], v[52:55]
	v_mfma_f32_16x16x32_bf16 v[48:51], v[170:173], v[178:181], v[48:51]
	v_mfma_f32_16x16x32_bf16 v[36:39], v[162:165], v[186:189], v[36:39]
	v_mfma_f32_16x16x32_bf16 v[32:35], v[170:173], v[186:189], v[32:35]
	v_mfma_f32_16x16x32_bf16 v[20:23], v[162:165], v[194:197], v[20:23]
	v_mfma_f32_16x16x32_bf16 v[16:19], v[170:173], v[194:197], v[16:19]
	v_mfma_f32_16x16x32_bf16 v[4:7], v[162:165], v[202:205], v[4:7]
	v_mfma_f32_16x16x32_bf16 v[0:3], v[170:173], v[202:205], v[0:3]
	s_barrier
	s_addk_i32 s44, 0x200
	s_add_u32 s76, s76, 0x100
	s_addc_u32 s77, s77, 0
	s_add_i32 s22, s82, 2
	v_lshl_add_u64 v[136:137], v[136:137], 0, s[58:59]
	s_cmp_gt_u32 s82, 29
	v_lshl_add_u64 v[134:135], v[134:135], 0, s[58:59]
	s_cbranch_scc1 .LBB0_1261
	s_mov_b32 s82, s22
	s_branch .LBB0_1257
.LBB0_1261:
	s_setprio 0
	s_and_b64 vcc, exec, s[86:87]
	s_cbranch_vccz .LBB0_1263
	s_barrier
